# GEMM K-loop heads aligned to 64 bytes (instruction-fetch phase pin) on all six GEMM loops
# baseline (speedup 1.0000x reference)
; template <class Epi, class Sched>
; __device__ __forceinline__ void gemm_phase(LAS unsigned char* lds, const Gemm g, const Sched& S, const Epi& E) {
;     ...
;         const bool has_next = S.next(ui + 1, nxt);
;         const char* nA = has_next ? (const char*)g.A + (size_t)nxt.seg * g.segA + (size_t)nxt.pm * tstepA : cA;
;         const char* nB = has_next ? (const char*)g.Bt + (size_t)nxt.seg * g.segB + (size_t)nxt.pn * tstepB : cB;
;         const int ntu = cur.nt ? cur.nt : nt;
;         for (int t = 0; t < ntu; t += 2) {
;             const bool last = (t == ntu - 2);
;             const char* a1 = cA + (size_t)(t + 1) * kstep;
;             const char* a2 = last ? nA : cA + (size_t)(t + 2) * kstep; const char* b2 = last ? nB : cB + (size_t)(t + 2) * kstep;
;             const char* a3 = a2 + kstep; const char* b3 = b2 + kstep;
;     ...
;         if (!E.keep(cur)) {
; #pragma unroll
;             for (int a = 0; a < 2; ++a)
; #pragma unroll
;                 for (int b = 0; b < 2; ++b)
; #pragma unroll
;                     for (int m = 0; m < 4; ++m)
; #pragma unroll
;                         for (int n = 0; n < 2; ++n) acc[a][b][m][n] = (f32x4){0.f, 0.f, 0.f, 0.f};
;         }
;         cur = nxt; cA = nA; cB = nB; ++ui;
.LBB0_380:
	v_mov_b64_e32 v[2:3], 0xd00
	s_ashr_i32 s25, s24, 31
	v_cmp_lt_i64_e32 vcc, s[26:27], v[2:3]
	s_lshl_b64 s[26:27], s[24:25], 20
	s_add_u32 s26, s58, s26
	s_addc_u32 s27, s59, s27
	s_and_b64 s[28:29], vcc, exec
	s_cselect_b32 s1, s27, s13
	s_cselect_b32 s25, s26, s12
	s_ashr_i32 s23, s22, 31
	s_lshl_b64 s[28:29], s[22:23], 20
	s_add_u32 s50, s56, s28
	s_addc_u32 s51, s57, s29
	s_and_b64 s[28:29], vcc, exec
	s_cselect_b32 s23, s51, s53
	s_cselect_b32 s28, s50, s52
	s_add_u32 s12, s12, 0x80080
	s_addc_u32 s13, s13, 0
	s_add_u32 s29, s52, 0x100
	v_mov_b32_e32 v2, 0
	s_addc_u32 s30, s53, 0
	s_mov_b32 s36, -2
	v_mov_b32_e32 v3, v2
	v_mov_b32_e32 v4, v2
	v_mov_b32_e32 v5, v2
	v_mov_b32_e32 v6, v2
	s_waitcnt lgkmcnt(0)
	v_mov_b32_e32 v7, v2
	v_mov_b32_e32 v8, v2
	v_mov_b32_e32 v9, v2
	v_mov_b32_e32 v18, v2
	v_mov_b32_e32 v19, v2
	v_mov_b32_e32 v20, v2
	v_mov_b32_e32 v21, v2
	v_mov_b32_e32 v22, v2
	v_mov_b32_e32 v23, v2
	v_mov_b32_e32 v24, v2
	v_mov_b32_e32 v25, v2
	v_mov_b32_e32 v34, v2
	v_mov_b32_e32 v35, v2
	v_mov_b32_e32 v36, v2
	v_mov_b32_e32 v37, v2
	v_mov_b32_e32 v38, v2
	v_mov_b32_e32 v39, v2
	v_mov_b32_e32 v40, v2
	v_mov_b32_e32 v41, v2
	v_mov_b32_e32 v50, v2
	v_mov_b32_e32 v51, v2
	v_mov_b32_e32 v52, v2
	v_mov_b32_e32 v53, v2
	v_mov_b32_e32 v54, v2
	v_mov_b32_e32 v55, v2
	v_mov_b32_e32 v56, v2
	v_mov_b32_e32 v57, v2
	v_mov_b32_e32 v10, v2
	v_mov_b32_e32 v11, v2
	v_mov_b32_e32 v12, v2
	v_mov_b32_e32 v13, v2
	v_mov_b32_e32 v14, v2
	v_mov_b32_e32 v15, v2
	v_mov_b32_e32 v16, v2
	v_mov_b32_e32 v17, v2
	v_mov_b32_e32 v26, v2
	v_mov_b32_e32 v27, v2
	v_mov_b32_e32 v28, v2
	v_mov_b32_e32 v29, v2
	v_mov_b32_e32 v30, v2
	v_mov_b32_e32 v31, v2
	v_mov_b32_e32 v32, v2
	v_mov_b32_e32 v33, v2
	v_mov_b32_e32 v42, v2
	v_mov_b32_e32 v43, v2
	v_mov_b32_e32 v44, v2
	v_mov_b32_e32 v45, v2
	v_mov_b32_e32 v46, v2
	v_mov_b32_e32 v47, v2
	v_mov_b32_e32 v48, v2
	v_mov_b32_e32 v49, v2
	v_mov_b32_e32 v58, v2
	v_mov_b32_e32 v59, v2
	v_mov_b32_e32 v60, v2
	v_mov_b32_e32 v61, v2
	v_mov_b32_e32 v62, v2
	v_mov_b32_e32 v63, v2
	v_mov_b32_e32 v64, v2
	v_mov_b32_e32 v65, v2
	v_mov_b32_e32 v66, v2
	v_mov_b32_e32 v67, v2
	v_mov_b32_e32 v68, v2
	v_mov_b32_e32 v69, v2
	v_mov_b32_e32 v70, v2
	v_mov_b32_e32 v71, v2
	v_mov_b32_e32 v72, v2
	v_mov_b32_e32 v73, v2
	v_mov_b32_e32 v82, v2
	v_mov_b32_e32 v83, v2
	v_mov_b32_e32 v84, v2
	v_mov_b32_e32 v85, v2
	v_mov_b32_e32 v86, v2
	v_mov_b32_e32 v87, v2
	v_mov_b32_e32 v88, v2
	v_mov_b32_e32 v89, v2
	v_mov_b32_e32 v98, v2
	v_mov_b32_e32 v99, v2
	v_mov_b32_e32 v100, v2
	v_mov_b32_e32 v101, v2
	v_mov_b32_e32 v102, v2
	v_mov_b32_e32 v103, v2
	v_mov_b32_e32 v104, v2
	v_mov_b32_e32 v105, v2
	v_mov_b32_e32 v114, v2
	v_mov_b32_e32 v115, v2
	v_mov_b32_e32 v116, v2
	v_mov_b32_e32 v117, v2
	v_mov_b32_e32 v118, v2
	v_mov_b32_e32 v119, v2
	v_mov_b32_e32 v120, v2
	v_mov_b32_e32 v121, v2
	v_mov_b32_e32 v74, v2
	v_mov_b32_e32 v75, v2
	v_mov_b32_e32 v76, v2
	v_mov_b32_e32 v77, v2
	v_mov_b32_e32 v78, v2
	v_mov_b32_e32 v79, v2
	v_mov_b32_e32 v80, v2
	v_mov_b32_e32 v81, v2
	v_mov_b32_e32 v90, v2
	v_mov_b32_e32 v91, v2
	v_mov_b32_e32 v92, v2
	v_mov_b32_e32 v93, v2
	v_mov_b32_e32 v94, v2
	v_mov_b32_e32 v95, v2
	v_mov_b32_e32 v96, v2
	v_mov_b32_e32 v97, v2
	v_mov_b32_e32 v106, v2
	v_mov_b32_e32 v107, v2
	v_mov_b32_e32 v108, v2
	v_mov_b32_e32 v109, v2
	v_mov_b32_e32 v110, v2
	v_mov_b32_e32 v111, v2
	v_mov_b32_e32 v112, v2
	v_mov_b32_e32 v113, v2
	v_mov_b32_e32 v122, v2
	v_mov_b32_e32 v123, v2
	v_mov_b32_e32 v124, v2
	v_mov_b32_e32 v125, v2
	v_mov_b32_e32 v126, v2
	v_mov_b32_e32 v127, v2
	v_mov_b32_e32 v128, v2
	v_mov_b32_e32 v129, v2
	v_add_u32_e32 v240, 0x10000, v170
	.p2align	6

; template <class Epi, class Sched>
; __device__ __forceinline__ void gemm_phase(LAS unsigned char* lds, const Gemm g, const Sched& S, const Epi& E) {
;     ...
;         const bool has_next = S.next(ui + 1, nxt);
;         const char* nA = has_next ? (const char*)g.A + (size_t)nxt.seg * g.segA + (size_t)nxt.pm * tstepA : cA;
;         const char* nB = has_next ? (const char*)g.Bt + (size_t)nxt.seg * g.segB + (size_t)nxt.pn * tstepB : cB;
;         const int ntu = cur.nt ? cur.nt : nt;
;         for (int t = 0; t < ntu; t += 2) {
;             const bool last = (t == ntu - 2);
;             const char* a1 = cA + (size_t)(t + 1) * kstep;
;             const char* a2 = last ? nA : cA + (size_t)(t + 2) * kstep; const char* b2 = last ? nB : cB + (size_t)(t + 2) * kstep;
;             const char* a3 = a2 + kstep; const char* b3 = b2 + kstep;
;     ...
;         if (!E.keep(cur)) {
; #pragma unroll
;             for (int a = 0; a < 2; ++a)
; #pragma unroll
;                 for (int b = 0; b < 2; ++b)
; #pragma unroll
;                     for (int m = 0; m < 4; ++m)
; #pragma unroll
;                         for (int n = 0; n < 2; ++n) acc[a][b][m][n] = (f32x4){0.f, 0.f, 0.f, 0.f};
;         }
;         cur = nxt; cA = nA; cB = nB; ++ui;
.LBB0_570:
	s_ashr_i32 s51, s50, 31
	s_lshl_b64 s[28:29], s[50:51], 18
	s_add_u32 s54, s36, s28
	s_addc_u32 s55, s37, s29
	s_and_b64 s[6:7], s[6:7], exec
	s_cselect_b32 s28, s55, s59
	s_cselect_b32 s29, s54, s58
	s_add_u32 s30, s58, 0x100
	v_mov_b32_e32 v2, 0
	s_addc_u32 s51, s59, 0
	s_mov_b32 s76, -2
	v_mov_b32_e32 v3, v2
	v_mov_b32_e32 v4, v2
	v_mov_b32_e32 v5, v2
	v_mov_b32_e32 v6, v2
	v_mov_b32_e32 v7, v2
	v_mov_b32_e32 v8, v2
	v_mov_b32_e32 v9, v2
	v_mov_b32_e32 v10, v2
	v_mov_b32_e32 v11, v2
	v_mov_b32_e32 v12, v2
	v_mov_b32_e32 v13, v2
	v_mov_b32_e32 v14, v2
	v_mov_b32_e32 v15, v2
	v_mov_b32_e32 v16, v2
	v_mov_b32_e32 v17, v2
	v_mov_b32_e32 v18, v2
	v_mov_b32_e32 v19, v2
	v_mov_b32_e32 v20, v2
	v_mov_b32_e32 v21, v2
	v_mov_b32_e32 v22, v2
	v_mov_b32_e32 v23, v2
	v_mov_b32_e32 v24, v2
	v_mov_b32_e32 v25, v2
	v_mov_b32_e32 v26, v2
	v_mov_b32_e32 v27, v2
	v_mov_b32_e32 v28, v2
	v_mov_b32_e32 v29, v2
	v_mov_b32_e32 v30, v2
	v_mov_b32_e32 v31, v2
	v_mov_b32_e32 v32, v2
	v_mov_b32_e32 v33, v2
	v_mov_b32_e32 v34, v2
	v_mov_b32_e32 v35, v2
	v_mov_b32_e32 v36, v2
	v_mov_b32_e32 v37, v2
	v_mov_b32_e32 v38, v2
	v_mov_b32_e32 v39, v2
	v_mov_b32_e32 v40, v2
	v_mov_b32_e32 v41, v2
	v_mov_b32_e32 v42, v2
	v_mov_b32_e32 v43, v2
	v_mov_b32_e32 v44, v2
	v_mov_b32_e32 v45, v2
	v_mov_b32_e32 v46, v2
	v_mov_b32_e32 v47, v2
	v_mov_b32_e32 v48, v2
	v_mov_b32_e32 v49, v2
	v_mov_b32_e32 v50, v2
	v_mov_b32_e32 v51, v2
	v_mov_b32_e32 v52, v2
	v_mov_b32_e32 v53, v2
	v_mov_b32_e32 v54, v2
	v_mov_b32_e32 v55, v2
	v_mov_b32_e32 v56, v2
	v_mov_b32_e32 v57, v2
	v_mov_b32_e32 v58, v2
	v_mov_b32_e32 v59, v2
	v_mov_b32_e32 v60, v2
	v_mov_b32_e32 v61, v2
	v_mov_b32_e32 v62, v2
	v_mov_b32_e32 v63, v2
	v_mov_b32_e32 v64, v2
	v_mov_b32_e32 v65, v2
	v_mov_b32_e32 v66, v2
	v_mov_b32_e32 v67, v2
	v_mov_b32_e32 v68, v2
	v_mov_b32_e32 v69, v2
	v_mov_b32_e32 v70, v2
	v_mov_b32_e32 v71, v2
	v_mov_b32_e32 v72, v2
	v_mov_b32_e32 v73, v2
	v_mov_b32_e32 v74, v2
	v_mov_b32_e32 v75, v2
	v_mov_b32_e32 v76, v2
	v_mov_b32_e32 v77, v2
	v_mov_b32_e32 v78, v2
	v_mov_b32_e32 v79, v2
	v_mov_b32_e32 v80, v2
	v_mov_b32_e32 v81, v2
	v_mov_b32_e32 v82, v2
	v_mov_b32_e32 v83, v2
	v_mov_b32_e32 v84, v2
	v_mov_b32_e32 v85, v2
	v_mov_b32_e32 v86, v2
	v_mov_b32_e32 v87, v2
	v_mov_b32_e32 v88, v2
	v_mov_b32_e32 v89, v2
	v_mov_b32_e32 v90, v2
	v_mov_b32_e32 v91, v2
	v_mov_b32_e32 v92, v2
	v_mov_b32_e32 v93, v2
	v_mov_b32_e32 v94, v2
	v_mov_b32_e32 v95, v2
	v_mov_b32_e32 v96, v2
	v_mov_b32_e32 v97, v2
	v_mov_b32_e32 v98, v2
	v_mov_b32_e32 v99, v2
	v_mov_b32_e32 v100, v2
	v_mov_b32_e32 v101, v2
	v_mov_b32_e32 v102, v2
	v_mov_b32_e32 v103, v2
	v_mov_b32_e32 v104, v2
	v_mov_b32_e32 v105, v2
	v_mov_b32_e32 v106, v2
	v_mov_b32_e32 v107, v2
	v_mov_b32_e32 v108, v2
	v_mov_b32_e32 v109, v2
	v_mov_b32_e32 v110, v2
	v_mov_b32_e32 v111, v2
	v_mov_b32_e32 v112, v2
	v_mov_b32_e32 v113, v2
	v_mov_b32_e32 v114, v2
	v_mov_b32_e32 v115, v2
	v_mov_b32_e32 v116, v2
	v_mov_b32_e32 v117, v2
	v_mov_b32_e32 v118, v2
	v_mov_b32_e32 v119, v2
	v_mov_b32_e32 v120, v2
	v_mov_b32_e32 v121, v2
	v_mov_b32_e32 v122, v2
	v_mov_b32_e32 v123, v2
	v_mov_b32_e32 v124, v2
	v_mov_b32_e32 v125, v2
	v_mov_b32_e32 v126, v2
	v_mov_b32_e32 v127, v2
	v_mov_b32_e32 v128, v2
	v_mov_b32_e32 v129, v2
	v_add_u32_e32 v240, 0x10000, v197
	.p2align	6

; template <class Epi, class Sched>
; __device__ __forceinline__ void gemm_phase(LAS unsigned char* lds, const Gemm g, const Sched& S, const Epi& E) {
;     ...
;         const char* nA = has_next ? (const char*)g.A + (size_t)nxt.seg * g.segA + (size_t)nxt.pm * tstepA : cA;
;         const char* nB = has_next ? (const char*)g.Bt + (size_t)nxt.seg * g.segB + (size_t)nxt.pn * tstepB : cB;
;         const int ntu = cur.nt ? cur.nt : nt;
;         for (int t = 0; t < ntu; t += 2) {
;             const bool last = (t == ntu - 2);
;             const char* a1 = cA + (size_t)(t + 1) * kstep;
;             const char* a2 = last ? nA : cA + (size_t)(t + 2) * kstep; const char* b2 = last ? nB : cB + (size_t)(t + 2) * kstep;
;             const char* a3 = a2 + kstep; const char* b3 = b2 + kstep;
;             if (last && has_next) S.a_ready(nxt);
.LBB0_870:
	s_lshl_b64 s[28:29], s[54:55], 22
	s_add_u32 s6, s38, s28
	s_addc_u32 s7, s72, s29
	s_ashr_i32 s63, s62, 31
	s_lshl_b64 s[28:29], s[62:63], 19
	s_add_u32 s70, s6, s28
	s_addc_u32 s71, s7, s29
	s_and_b64 s[28:29], s[52:53], exec
	s_cselect_b32 s13, s71, s27
	s_cselect_b32 s21, s70, s26
	s_cmp_lg_u32 s1, 0
	s_cselect_b64 vcc, -1, 0
	s_cmp_eq_u32 s1, 0
	s_cselect_b64 s[64:65], -1, 0
	s_and_b64 s[6:7], s[64:65], exec
	s_cselect_b32 s1, 16, s1
	s_add_i32 s23, s1, -2
	s_add_u32 s68, s68, 0x40080
	s_addc_u32 s69, s69, 0
	s_add_u32 s55, s26, 0x100
	s_mov_b32 s28, 0
	s_addc_u32 s59, s27, 0
	v_add_u32_e32 v240, 0x10000, v207
	.p2align	6

; template <class Epi, class Sched>
; __device__ __forceinline__ void gemm_phase(LAS unsigned char* lds, const Gemm g, const Sched& S, const Epi& E) {
;     ...
;         const int ntu = cur.nt ? cur.nt : nt;
;         for (int t = 0; t < ntu; t += 2) {
;             const bool last = (t == ntu - 2);
;             const char* a1 = cA + (size_t)(t + 1) * kstep;
;             const char* a2 = last ? nA : cA + (size_t)(t + 2) * kstep; const char* b2 = last ? nB : cB + (size_t)(t + 2) * kstep;
;             const char* a3 = a2 + kstep; const char* b3 = b2 + kstep;
;     ...
;         if (!E.keep(cur)) {
; #pragma unroll
;             for (int a = 0; a < 2; ++a)
; #pragma unroll
;                 for (int b = 0; b < 2; ++b)
; #pragma unroll
;                     for (int m = 0; m < 4; ++m)
; #pragma unroll
;                         for (int n = 0; n < 2; ++n) acc[a][b][m][n] = (f32x4){0.f, 0.f, 0.f, 0.f};
;         }
.LBB0_983:
	s_cmp_lg_u32 s28, 0
	s_cselect_b64 s[50:51], -1, 0
	s_and_b64 s[56:57], s[50:51], exec
	s_cselect_b32 s17, s28, 32
	s_cmp_lt_i32 s17, 1
	s_cbranch_scc1 .LBB0_987
	s_add_i32 s21, s17, -2
	s_add_u32 s70, s54, 0x100
	v_mov_b32_e32 v2, 0
	s_addc_u32 s71, s55, 0
	s_mov_b32 s28, 0
	v_mov_b32_e32 v3, v2
	v_mov_b32_e32 v4, v2
	v_mov_b32_e32 v5, v2
	v_mov_b32_e32 v6, v2
	v_mov_b32_e32 v7, v2
	v_mov_b32_e32 v8, v2
	v_mov_b32_e32 v9, v2
	v_mov_b32_e32 v18, v2
	v_mov_b32_e32 v19, v2
	v_mov_b32_e32 v20, v2
	v_mov_b32_e32 v21, v2
	v_mov_b32_e32 v22, v2
	v_mov_b32_e32 v23, v2
	v_mov_b32_e32 v24, v2
	v_mov_b32_e32 v25, v2
	v_mov_b32_e32 v34, v2
	v_mov_b32_e32 v35, v2
	v_mov_b32_e32 v36, v2
	v_mov_b32_e32 v37, v2
	v_mov_b32_e32 v38, v2
	v_mov_b32_e32 v39, v2
	v_mov_b32_e32 v40, v2
	v_mov_b32_e32 v41, v2
	v_mov_b32_e32 v50, v2
	v_mov_b32_e32 v51, v2
	v_mov_b32_e32 v52, v2
	v_mov_b32_e32 v53, v2
	v_mov_b32_e32 v54, v2
	v_mov_b32_e32 v55, v2
	v_mov_b32_e32 v56, v2
	v_mov_b32_e32 v57, v2
	v_mov_b32_e32 v10, v2
	v_mov_b32_e32 v11, v2
	v_mov_b32_e32 v12, v2
	v_mov_b32_e32 v13, v2
	v_mov_b32_e32 v14, v2
	v_mov_b32_e32 v15, v2
	v_mov_b32_e32 v16, v2
	v_mov_b32_e32 v17, v2
	v_mov_b32_e32 v26, v2
	v_mov_b32_e32 v27, v2
	v_mov_b32_e32 v28, v2
	v_mov_b32_e32 v29, v2
	v_mov_b32_e32 v30, v2
	v_mov_b32_e32 v31, v2
	v_mov_b32_e32 v32, v2
	v_mov_b32_e32 v33, v2
	v_mov_b32_e32 v42, v2
	v_mov_b32_e32 v43, v2
	v_mov_b32_e32 v44, v2
	v_mov_b32_e32 v45, v2
	v_mov_b32_e32 v46, v2
	v_mov_b32_e32 v47, v2
	v_mov_b32_e32 v48, v2
	v_mov_b32_e32 v49, v2
	v_mov_b32_e32 v58, v2
	v_mov_b32_e32 v59, v2
	v_mov_b32_e32 v60, v2
	v_mov_b32_e32 v61, v2
	v_mov_b32_e32 v62, v2
	v_mov_b32_e32 v63, v2
	v_mov_b32_e32 v64, v2
	v_mov_b32_e32 v65, v2
	v_mov_b32_e32 v66, v2
	v_mov_b32_e32 v67, v2
	v_mov_b32_e32 v68, v2
	v_mov_b32_e32 v69, v2
	v_mov_b32_e32 v70, v2
	v_mov_b32_e32 v71, v2
	v_mov_b32_e32 v72, v2
	v_mov_b32_e32 v73, v2
	v_mov_b32_e32 v82, v2
	v_mov_b32_e32 v83, v2
	v_mov_b32_e32 v84, v2
	v_mov_b32_e32 v85, v2
	v_mov_b32_e32 v86, v2
	v_mov_b32_e32 v87, v2
	v_mov_b32_e32 v88, v2
	v_mov_b32_e32 v89, v2
	v_mov_b32_e32 v98, v2
	v_mov_b32_e32 v99, v2
	v_mov_b32_e32 v100, v2
	v_mov_b32_e32 v101, v2
	v_mov_b32_e32 v102, v2
	v_mov_b32_e32 v103, v2
	v_mov_b32_e32 v104, v2
	v_mov_b32_e32 v105, v2
	v_mov_b32_e32 v114, v2
	v_mov_b32_e32 v115, v2
	v_mov_b32_e32 v116, v2
	v_mov_b32_e32 v117, v2
	v_mov_b32_e32 v118, v2
	v_mov_b32_e32 v119, v2
	v_mov_b32_e32 v120, v2
	v_mov_b32_e32 v121, v2
	v_mov_b32_e32 v74, v2
	v_mov_b32_e32 v75, v2
	v_mov_b32_e32 v76, v2
	v_mov_b32_e32 v77, v2
	v_mov_b32_e32 v78, v2
	v_mov_b32_e32 v79, v2
	v_mov_b32_e32 v80, v2
	v_mov_b32_e32 v81, v2
	v_mov_b32_e32 v90, v2
	v_mov_b32_e32 v91, v2
	v_mov_b32_e32 v92, v2
	v_mov_b32_e32 v93, v2
	v_mov_b32_e32 v94, v2
	v_mov_b32_e32 v95, v2
	v_mov_b32_e32 v96, v2
	v_mov_b32_e32 v97, v2
	v_mov_b32_e32 v106, v2
	v_mov_b32_e32 v107, v2
	v_mov_b32_e32 v108, v2
	v_mov_b32_e32 v109, v2
	v_mov_b32_e32 v110, v2
	v_mov_b32_e32 v111, v2
	v_mov_b32_e32 v112, v2
	v_mov_b32_e32 v113, v2
	v_mov_b32_e32 v122, v2
	v_mov_b32_e32 v123, v2
	v_mov_b32_e32 v124, v2
	v_mov_b32_e32 v125, v2
	v_mov_b32_e32 v126, v2
	v_mov_b32_e32 v127, v2
	v_mov_b32_e32 v128, v2
	v_mov_b32_e32 v129, v2
	v_add_u32_e32 v240, 0x10000, v141
	.p2align	6

; template <class Epi, class Sched>
; __device__ __forceinline__ void gemm_phase(LAS unsigned char* lds, const Gemm g, const Sched& S, const Epi& E) {
;     ...
;         const bool has_next = S.next(ui + 1, nxt);
;         const char* nA = has_next ? (const char*)g.A + (size_t)nxt.seg * g.segA + (size_t)nxt.pm * tstepA : cA;
;         const char* nB = has_next ? (const char*)g.Bt + (size_t)nxt.seg * g.segB + (size_t)nxt.pn * tstepB : cB;
;         const int ntu = cur.nt ? cur.nt : nt;
;         for (int t = 0; t < ntu; t += 2) {
;             const bool last = (t == ntu - 2);
;             const char* a1 = cA + (size_t)(t + 1) * kstep;
;             const char* a2 = last ? nA : cA + (size_t)(t + 2) * kstep; const char* b2 = last ? nB : cB + (size_t)(t + 2) * kstep;
;             const char* a3 = a2 + kstep; const char* b3 = b2 + kstep;
;     ...
;         if (!E.keep(cur)) {
; #pragma unroll
;             for (int a = 0; a < 2; ++a)
; #pragma unroll
;                 for (int b = 0; b < 2; ++b)
; #pragma unroll
;                     for (int m = 0; m < 4; ++m)
; #pragma unroll
;                         for (int n = 0; n < 2; ++n) acc[a][b][m][n] = (f32x4){0.f, 0.f, 0.f, 0.f};
;         }
;         cur = nxt; cA = nA; cB = nB; ++ui;
.LBB0_1139:
	v_mov_b64_e32 v[2:3], s[30:31]
	s_ashr_i32 s13, s12, 31
	v_cmp_lt_i64_e32 vcc, s[16:17], v[2:3]
	s_lshl_b64 s[16:17], s[12:13], 20
	s_add_u32 s16, s36, s16
	s_addc_u32 s17, s37, s17
	s_and_b64 s[20:21], vcc, exec
	s_cselect_b32 s13, s17, s27
	s_cselect_b32 s57, s16, s26
	s_ashr_i32 s11, s10, 31
	s_lshl_b64 s[20:21], s[10:11], 20
	s_add_u32 s20, s38, s20
	s_addc_u32 s21, s39, s21
	s_and_b64 s[28:29], vcc, exec
	s_cselect_b32 s11, s21, s51
	s_cselect_b32 s58, s20, s50
	s_add_u32 s26, s26, 0x80080
	s_addc_u32 s27, s27, 0
	s_add_u32 s59, s50, 0x100
	v_mov_b32_e32 v2, 0
	s_addc_u32 s62, s51, 0
	s_mov_b32 s63, -2
	v_mov_b32_e32 v3, v2
	v_mov_b32_e32 v4, v2
	v_mov_b32_e32 v5, v2
	v_mov_b32_e32 v10, v2
	v_mov_b32_e32 v11, v2
	v_mov_b32_e32 v12, v2
	v_mov_b32_e32 v13, v2
	v_mov_b32_e32 v18, v2
	v_mov_b32_e32 v19, v2
	v_mov_b32_e32 v20, v2
	v_mov_b32_e32 v21, v2
	v_mov_b32_e32 v26, v2
	v_mov_b32_e32 v27, v2
	v_mov_b32_e32 v28, v2
	v_mov_b32_e32 v29, v2
	v_mov_b32_e32 v34, v2
	v_mov_b32_e32 v35, v2
	v_mov_b32_e32 v36, v2
	v_mov_b32_e32 v37, v2
	v_mov_b32_e32 v42, v2
	v_mov_b32_e32 v43, v2
	v_mov_b32_e32 v44, v2
	v_mov_b32_e32 v45, v2
	v_mov_b32_e32 v50, v2
	v_mov_b32_e32 v51, v2
	v_mov_b32_e32 v52, v2
	v_mov_b32_e32 v53, v2
	v_mov_b32_e32 v58, v2
	v_mov_b32_e32 v59, v2
	v_mov_b32_e32 v60, v2
	v_mov_b32_e32 v61, v2
	v_mov_b32_e32 v6, v2
	v_mov_b32_e32 v7, v2
	v_mov_b32_e32 v8, v2
	v_mov_b32_e32 v9, v2
	v_mov_b32_e32 v14, v2
	v_mov_b32_e32 v15, v2
	v_mov_b32_e32 v16, v2
	v_mov_b32_e32 v17, v2
	v_mov_b32_e32 v22, v2
	v_mov_b32_e32 v23, v2
	v_mov_b32_e32 v24, v2
	v_mov_b32_e32 v25, v2
	v_mov_b32_e32 v30, v2
	v_mov_b32_e32 v31, v2
	v_mov_b32_e32 v32, v2
	v_mov_b32_e32 v33, v2
	v_mov_b32_e32 v38, v2
	v_mov_b32_e32 v39, v2
	v_mov_b32_e32 v40, v2
	v_mov_b32_e32 v41, v2
	v_mov_b32_e32 v46, v2
	v_mov_b32_e32 v47, v2
	v_mov_b32_e32 v48, v2
	v_mov_b32_e32 v49, v2
	v_mov_b32_e32 v54, v2
	v_mov_b32_e32 v55, v2
	v_mov_b32_e32 v56, v2
	v_mov_b32_e32 v57, v2
	v_mov_b32_e32 v62, v2
	v_mov_b32_e32 v63, v2
	v_mov_b32_e32 v64, v2
	v_mov_b32_e32 v65, v2
	v_mov_b32_e32 v66, v2
	v_mov_b32_e32 v67, v2
	v_mov_b32_e32 v68, v2
	v_mov_b32_e32 v69, v2
	v_mov_b32_e32 v74, v2
	v_mov_b32_e32 v75, v2
	v_mov_b32_e32 v76, v2
	v_mov_b32_e32 v77, v2
	v_mov_b32_e32 v82, v2
	v_mov_b32_e32 v83, v2
	v_mov_b32_e32 v84, v2
	v_mov_b32_e32 v85, v2
	v_mov_b32_e32 v90, v2
	v_mov_b32_e32 v91, v2
	v_mov_b32_e32 v92, v2
	v_mov_b32_e32 v93, v2
	v_mov_b32_e32 v98, v2
	v_mov_b32_e32 v99, v2
	v_mov_b32_e32 v100, v2
	v_mov_b32_e32 v101, v2
	v_mov_b32_e32 v106, v2
	v_mov_b32_e32 v107, v2
	v_mov_b32_e32 v108, v2
	v_mov_b32_e32 v109, v2
	v_mov_b32_e32 v114, v2
	v_mov_b32_e32 v115, v2
	v_mov_b32_e32 v116, v2
	v_mov_b32_e32 v117, v2
	v_mov_b32_e32 v122, v2
	v_mov_b32_e32 v123, v2
	v_mov_b32_e32 v124, v2
	v_mov_b32_e32 v125, v2
	v_mov_b32_e32 v70, v2
	v_mov_b32_e32 v71, v2
	v_mov_b32_e32 v72, v2
	v_mov_b32_e32 v73, v2
	v_mov_b32_e32 v78, v2
	v_mov_b32_e32 v79, v2
	v_mov_b32_e32 v80, v2
	v_mov_b32_e32 v81, v2
	v_mov_b32_e32 v86, v2
	v_mov_b32_e32 v87, v2
	v_mov_b32_e32 v88, v2
	v_mov_b32_e32 v89, v2
	v_mov_b32_e32 v94, v2
	v_mov_b32_e32 v95, v2
	v_mov_b32_e32 v96, v2
	v_mov_b32_e32 v97, v2
	v_mov_b32_e32 v102, v2
	v_mov_b32_e32 v103, v2
	v_mov_b32_e32 v104, v2
	v_mov_b32_e32 v105, v2
	v_mov_b32_e32 v110, v2
	v_mov_b32_e32 v111, v2
	v_mov_b32_e32 v112, v2
	v_mov_b32_e32 v113, v2
	v_mov_b32_e32 v118, v2
	v_mov_b32_e32 v119, v2
	v_mov_b32_e32 v120, v2
	v_mov_b32_e32 v121, v2
	v_mov_b32_e32 v126, v2
	v_mov_b32_e32 v127, v2
	v_mov_b32_e32 v128, v2
	v_mov_b32_e32 v129, v2
	v_add_u32_e32 v240, 0x10000, v143
	.p2align	6

; template <class Epi, class Sched>
; __device__ __forceinline__ void gemm_phase(LAS unsigned char* lds, const Gemm g, const Sched& S, const Epi& E) {
;     ...
;         const int ntu = cur.nt ? cur.nt : nt;
;         for (int t = 0; t < ntu; t += 2) {
;             const bool last = (t == ntu - 2);
;             const char* a1 = cA + (size_t)(t + 1) * kstep;
;             const char* a2 = last ? nA : cA + (size_t)(t + 2) * kstep; const char* b2 = last ? nB : cB + (size_t)(t + 2) * kstep;
;             const char* a3 = a2 + kstep; const char* b3 = b2 + kstep;
;     ...
;         if (!E.keep(cur)) {
; #pragma unroll
;             for (int a = 0; a < 2; ++a)
; #pragma unroll
;                 for (int b = 0; b < 2; ++b)
; #pragma unroll
;                     for (int m = 0; m < 4; ++m)
; #pragma unroll
;                         for (int n = 0; n < 2; ++n) acc[a][b][m][n] = (f32x4){0.f, 0.f, 0.f, 0.f};
;         }
.LBB0_1236:
	s_cmp_lg_u32 s26, 0
	s_cselect_b64 s[20:21], -1, 0
	s_and_b64 s[28:29], s[20:21], exec
	s_cselect_b32 s68, s26, 0x58
	s_cmp_lt_i32 s68, 1
	s_cbranch_scc1 .LBB0_1240
	s_add_i32 s69, s68, -2
	s_add_u32 s70, s24, 0x100
	v_mov_b32_e32 v2, 0
	s_addc_u32 s71, s25, 0
	s_mov_b32 s26, 0
	v_mov_b32_e32 v3, v2
	v_mov_b32_e32 v4, v2
	v_mov_b32_e32 v5, v2
	v_mov_b32_e32 v6, v2
	v_mov_b32_e32 v7, v2
	v_mov_b32_e32 v8, v2
	v_mov_b32_e32 v9, v2
	v_mov_b32_e32 v18, v2
	v_mov_b32_e32 v19, v2
	v_mov_b32_e32 v20, v2
	v_mov_b32_e32 v21, v2
	v_mov_b32_e32 v22, v2
	v_mov_b32_e32 v23, v2
	v_mov_b32_e32 v24, v2
	v_mov_b32_e32 v25, v2
	v_mov_b32_e32 v34, v2
	v_mov_b32_e32 v35, v2
	v_mov_b32_e32 v36, v2
	v_mov_b32_e32 v37, v2
	v_mov_b32_e32 v38, v2
	v_mov_b32_e32 v39, v2
	v_mov_b32_e32 v40, v2
	v_mov_b32_e32 v41, v2
	v_mov_b32_e32 v50, v2
	v_mov_b32_e32 v51, v2
	v_mov_b32_e32 v52, v2
	v_mov_b32_e32 v53, v2
	v_mov_b32_e32 v54, v2
	v_mov_b32_e32 v55, v2
	v_mov_b32_e32 v56, v2
	v_mov_b32_e32 v57, v2
	v_mov_b32_e32 v10, v2
	v_mov_b32_e32 v11, v2
	v_mov_b32_e32 v12, v2
	v_mov_b32_e32 v13, v2
	v_mov_b32_e32 v14, v2
	v_mov_b32_e32 v15, v2
	v_mov_b32_e32 v16, v2
	v_mov_b32_e32 v17, v2
	v_mov_b32_e32 v26, v2
	v_mov_b32_e32 v27, v2
	v_mov_b32_e32 v28, v2
	v_mov_b32_e32 v29, v2
	v_mov_b32_e32 v30, v2
	v_mov_b32_e32 v31, v2
	v_mov_b32_e32 v32, v2
	v_mov_b32_e32 v33, v2
	v_mov_b32_e32 v42, v2
	v_mov_b32_e32 v43, v2
	v_mov_b32_e32 v44, v2
	v_mov_b32_e32 v45, v2
	v_mov_b32_e32 v46, v2
	v_mov_b32_e32 v47, v2
	v_mov_b32_e32 v48, v2
	v_mov_b32_e32 v49, v2
	v_mov_b32_e32 v58, v2
	v_mov_b32_e32 v59, v2
	v_mov_b32_e32 v60, v2
	v_mov_b32_e32 v61, v2
	v_mov_b32_e32 v62, v2
	v_mov_b32_e32 v63, v2
	v_mov_b32_e32 v64, v2
	v_mov_b32_e32 v65, v2
	v_mov_b32_e32 v66, v2
	v_mov_b32_e32 v67, v2
	v_mov_b32_e32 v68, v2
	v_mov_b32_e32 v69, v2
	v_mov_b32_e32 v70, v2
	v_mov_b32_e32 v71, v2
	v_mov_b32_e32 v72, v2
	v_mov_b32_e32 v73, v2
	v_mov_b32_e32 v82, v2
	v_mov_b32_e32 v83, v2
	v_mov_b32_e32 v84, v2
	v_mov_b32_e32 v85, v2
	v_mov_b32_e32 v86, v2
	v_mov_b32_e32 v87, v2
	v_mov_b32_e32 v88, v2
	v_mov_b32_e32 v89, v2
	v_mov_b32_e32 v98, v2
	v_mov_b32_e32 v99, v2
	v_mov_b32_e32 v100, v2
	v_mov_b32_e32 v101, v2
	v_mov_b32_e32 v102, v2
	v_mov_b32_e32 v103, v2
	v_mov_b32_e32 v104, v2
	v_mov_b32_e32 v105, v2
	v_mov_b32_e32 v114, v2
	v_mov_b32_e32 v115, v2
	v_mov_b32_e32 v116, v2
	v_mov_b32_e32 v117, v2
	v_mov_b32_e32 v118, v2
	v_mov_b32_e32 v119, v2
	v_mov_b32_e32 v120, v2
	v_mov_b32_e32 v121, v2
	v_mov_b32_e32 v74, v2
	v_mov_b32_e32 v75, v2
	v_mov_b32_e32 v76, v2
	v_mov_b32_e32 v77, v2
	v_mov_b32_e32 v78, v2
	v_mov_b32_e32 v79, v2
	v_mov_b32_e32 v80, v2
	v_mov_b32_e32 v81, v2
	v_mov_b32_e32 v90, v2
	v_mov_b32_e32 v91, v2
	v_mov_b32_e32 v92, v2
	v_mov_b32_e32 v93, v2
	v_mov_b32_e32 v94, v2
	v_mov_b32_e32 v95, v2
	v_mov_b32_e32 v96, v2
	v_mov_b32_e32 v97, v2
	v_mov_b32_e32 v106, v2
	v_mov_b32_e32 v107, v2
	v_mov_b32_e32 v108, v2
	v_mov_b32_e32 v109, v2
	v_mov_b32_e32 v110, v2
	v_mov_b32_e32 v111, v2
	v_mov_b32_e32 v112, v2
	v_mov_b32_e32 v113, v2
	v_mov_b32_e32 v122, v2
	v_mov_b32_e32 v123, v2
	v_mov_b32_e32 v124, v2
	v_mov_b32_e32 v125, v2
	v_mov_b32_e32 v126, v2
	v_mov_b32_e32 v127, v2
	v_mov_b32_e32 v128, v2
	v_mov_b32_e32 v129, v2
	v_add_u32_e32 v240, 0x10000, v141
	.p2align	6
